# barrier leader skips the L2 write-back after phases 3, 7, 13 (all stores write-through)
# baseline (speedup 1.0000x reference)
.LBB0_1042:
	v_cvt_f32_u32_e32 v4, v2
	v_sub_u32_e32 v3, 0, v2
	v_rcp_iflag_f32_e32 v4, v4
	s_nop 0
	v_mul_f32_e32 v4, 0x4f7ffffe, v4
	v_cvt_u32_f32_e32 v4, v4
	v_mul_lo_u32 v1, v3, v4
	v_mul_hi_u32 v1, v4, v1
	v_add_u32_e32 v1, v4, v1
	s_waitcnt vmcnt(0)
	v_mov_b32_e32 v5, v165
	v_mul_hi_u32 v1, v5, v1
	v_mul_lo_u32 v3, v1, v2
	v_sub_u32_e32 v3, v5, v3
	v_add_u32_e32 v4, 1, v1
	v_cmp_ge_u32_e32 vcc, v3, v2
	s_nop 1
	v_cndmask_b32_e32 v1, v1, v4, vcc
	v_sub_u32_e32 v4, v3, v2
	v_cndmask_b32_e32 v3, v3, v4, vcc
	v_add_u32_e32 v4, 1, v1
	v_cmp_ge_u32_e32 vcc, v3, v2
	v_add_u32_e32 v3, 1, v5
	s_nop 0
	v_cndmask_b32_e32 v1, v1, v4, vcc
	v_mul_lo_u32 v4, v2, v1
	v_add_u32_e32 v2, v4, v2
	v_cmp_ne_u32_e32 vcc, v3, v2
	s_waitcnt lgkmcnt(0)
	v_mad_u32_u24 v5, v1, v0, v0
	s_add_u32 s10, s90, 0x494e400
	s_addc_u32 s11, s91, 0
	s_cbranch_vccnz .Lgb_poll
	s_mov_b32 s2, 0x2088
	s_bitcmp1_b32 s2, s86
	s_cbranch_scc1 .Lgb_nowb
	buffer_wbl2 sc1
	s_waitcnt vmcnt(0)
